# attention and retention outputs stored write-through (sc1); mixer group barrier without L2 write-back
# baseline (speedup 1.0000x reference)
; DEVINL unsigned cvt_pk_bf16(float lo, float hi) { const f32x2 v = {lo, hi}; return __builtin_bit_cast(unsigned, __builtin_convertvector(v, bf16x2v)); }
; DEVINL void sb_task(const Ctx& c, int b, int hd, int qg) {
;     ...
;         for (int g = 0; g < 4; ++g) {
;             u32x2 pk; pk[0] = cvt_pk_bf16(o[d][4 * g], o[d][4 * g + 1]); pk[1] = cvt_pk_bf16(o[d][4 * g + 2], o[d][4 * g + 3]);
;             *(u32x2*)(yp + d * 32 + 8 * g + 4 * h) = pk;
;         }
; DEVINL void phase_mixers(const Ctx& c, int layer, unsigned char* lds) {
;     ...
;         for (int i = wid; i < 2 * NSB; i += nw) {
;             if (i < NSB) { const int qg = 67 - i / 64, bh = i & 63; sb_task(c, bh >> 3, bh & 7, qg); }
;             else { const int i2 = i - NSB; const int qg = 67 - i2 / 64, bh = i2 & 63; swa_task(c, layer, bh >> 3, bh & 7, qg); }
.LBB0_243:
	s_or_b64 exec, exec, s[52:53]
	v_readlane_b32 s1, v247, 42
	s_movk_i32 s0, 0x21ff
	global_store_dwordx2 v[2:3], v[0:1], off offset:112 sc1
	v_add_u32_e32 v168, s1, v168
	v_cmp_lt_i32_e32 vcc, s0, v168
	s_or_b64 s[50:51], vcc, s[50:51]
	v_add_u32_e32 v169, s1, v169
	s_andn2_b64 exec, exec, s[50:51]
	s_cbranch_execz .LBB0_265

; DEVINL unsigned cvt_pk_bf16(float lo, float hi) { const f32x2 v = {lo, hi}; return __builtin_bit_cast(unsigned, __builtin_convertvector(v, bf16x2v)); }
; DEVINL void swa_task(const Ctx& c, int layer, int b, int qh, int qg) {
;     ...
;     if (qg < 3) {
;         u32x2 z = {0u, 0u};
; #pragma unroll
;         for (int d = 0; d < 2; ++d)
; #pragma unroll
;             for (int g = 0; g < 4; ++g) *(u32x2*)(yp + d * 32 + 8 * g + 4 * h) = z;
;         return;
;     ...
;     const float inv = __builtin_amdgcn_rcpf(lrun);
; #pragma unroll
;     for (int d = 0; d < 2; ++d)
; #pragma unroll
;         for (int g = 0; g < 4; ++g) {
;             u32x2 pk; pk[0] = cvt_pk_bf16(o[d][4 * g] * inv, o[d][4 * g + 1] * inv); pk[1] = cvt_pk_bf16(o[d][4 * g + 2] * inv, o[d][4 * g + 3] * inv);
;             *(u32x2*)(yp + d * 32 + 8 * g + 4 * h) = pk;
;         }
.LBB0_252:
	s_or_b64 exec, exec, s[6:7]
	v_rcp_f32_e32 v32, v32
	v_mov_b32_e32 v93, v65
	v_lshl_add_u64 v[34:35], v[88:89], 0, v[92:93]
	v_pk_mul_f32 v[16:17], v[16:17], v[32:33] op_sel_hi:[1,0]
	v_pk_mul_f32 v[18:19], v[18:19], v[32:33] op_sel_hi:[1,0]
	s_nop 1
	v_pk_mul_f32 v[0:1], v[0:1], v[32:33] op_sel_hi:[1,0]
	v_pk_mul_f32 v[2:3], v[2:3], v[32:33] op_sel_hi:[1,0]
	v_cvt_pk_bf16_f32 v16, v16, v17
	v_cvt_pk_bf16_f32 v17, v18, v19
	v_cvt_pk_bf16_f32 v0, v0, v1
	v_cvt_pk_bf16_f32 v1, v2, v3
	global_store_dwordx2 v[34:35], v[16:17], off sc1
	v_pk_mul_f32 v[16:17], v[20:21], v[32:33] op_sel_hi:[1,0]
	v_pk_mul_f32 v[18:19], v[22:23], v[32:33] op_sel_hi:[1,0]
	global_store_dwordx2 v[34:35], v[0:1], off offset:64 sc1
	v_pk_mul_f32 v[0:1], v[4:5], v[32:33] op_sel_hi:[1,0]
	v_pk_mul_f32 v[2:3], v[6:7], v[32:33] op_sel_hi:[1,0]
	v_cvt_pk_bf16_f32 v16, v16, v17
	v_cvt_pk_bf16_f32 v17, v18, v19
	v_cvt_pk_bf16_f32 v0, v0, v1
	v_cvt_pk_bf16_f32 v1, v2, v3
	global_store_dwordx2 v[34:35], v[16:17], off offset:16 sc1
	v_pk_mul_f32 v[16:17], v[24:25], v[32:33] op_sel_hi:[1,0]
	v_pk_mul_f32 v[18:19], v[26:27], v[32:33] op_sel_hi:[1,0]
	global_store_dwordx2 v[34:35], v[0:1], off offset:80 sc1
	v_pk_mul_f32 v[0:1], v[8:9], v[32:33] op_sel_hi:[1,0]
	v_pk_mul_f32 v[2:3], v[10:11], v[32:33] op_sel_hi:[1,0]
	v_cvt_pk_bf16_f32 v16, v16, v17
	v_cvt_pk_bf16_f32 v17, v18, v19
	v_cvt_pk_bf16_f32 v0, v0, v1
	v_cvt_pk_bf16_f32 v1, v2, v3
	global_store_dwordx2 v[34:35], v[16:17], off offset:32 sc1
	v_pk_mul_f32 v[16:17], v[28:29], v[32:33] op_sel_hi:[1,0]
	v_pk_mul_f32 v[18:19], v[30:31], v[32:33] op_sel_hi:[1,0]
	global_store_dwordx2 v[34:35], v[0:1], off offset:96 sc1
	v_pk_mul_f32 v[0:1], v[12:13], v[32:33] op_sel_hi:[1,0]
	v_pk_mul_f32 v[2:3], v[14:15], v[32:33] op_sel_hi:[1,0]
	v_cvt_pk_bf16_f32 v16, v16, v17
	v_cvt_pk_bf16_f32 v17, v18, v19
	v_cvt_pk_bf16_f32 v0, v0, v1
	v_cvt_pk_bf16_f32 v1, v2, v3
	global_store_dwordx2 v[34:35], v[16:17], off offset:48 sc1
.LBB0_253:
	s_andn2_saveexec_b64 s[4:5], s[4:5]
	s_cbranch_execz .LBB0_255
	v_lshlrev_b32_e32 v64, 3, v40
	s_mov_b32 s66, s67
	v_lshl_add_u64 v[0:1], v[88:89], 0, v[64:65]
	v_mov_b64_e32 v[2:3], s[66:67]
	global_store_dwordx2 v[0:1], v[2:3], off sc1
	global_store_dwordx2 v[0:1], v[2:3], off offset:16 sc1
	global_store_dwordx2 v[0:1], v[2:3], off offset:32 sc1
	global_store_dwordx2 v[0:1], v[2:3], off offset:48 sc1
	global_store_dwordx2 v[0:1], v[2:3], off offset:64 sc1
	global_store_dwordx2 v[0:1], v[2:3], off offset:80 sc1
	global_store_dwordx2 v[0:1], v[2:3], off offset:96 sc1
	v_mov_b32_e32 v0, 0
	v_mov_b32_e32 v91, v65
	v_mov_b32_e32 v1, v0

; DEVINL unsigned cvt_pk_bf16(float lo, float hi) { const f32x2 v = {lo, hi}; return __builtin_bit_cast(unsigned, __builtin_convertvector(v, bf16x2v)); }
; DEVINL void sb_task(const Ctx& c, int b, int hd, int qg) {
;     ...
;     if (qg < 3) {
;         u32x2 z = {0u, 0u};
; #pragma unroll
;         for (int d = 0; d < 2; ++d)
; #pragma unroll
;             for (int g = 0; g < 4; ++g) *(u32x2*)(yp + d * 32 + 8 * g + 4 * h) = z;
;         return;
;     ...
; #pragma unroll
;     for (int d = 0; d < 2; ++d)
; #pragma unroll
;         for (int g = 0; g < 4; ++g) {
;             u32x2 pk; pk[0] = cvt_pk_bf16(o[d][4 * g], o[d][4 * g + 1]); pk[1] = cvt_pk_bf16(o[d][4 * g + 2], o[d][4 * g + 3]);
;             *(u32x2*)(yp + d * 32 + 8 * g + 4 * h) = pk;
;         }
.LBB0_262:
	s_or_b64 exec, exec, s[60:61]
	v_lshlrev_b32_e32 v64, 1, v90
	v_lshl_add_u64 v[32:33], v[88:89], 0, v[64:65]
	s_nop 5
	v_cvt_pk_bf16_f32 v0, v0, v1
	v_cvt_pk_bf16_f32 v1, v2, v3
	global_store_dwordx2 v[32:33], v[0:1], off sc1
	v_cvt_pk_bf16_f32 v0, v4, v5
	v_cvt_pk_bf16_f32 v1, v6, v7
	global_store_dwordx2 v[32:33], v[0:1], off offset:16 sc1
	v_cvt_pk_bf16_f32 v0, v8, v9
	v_cvt_pk_bf16_f32 v1, v10, v11
	global_store_dwordx2 v[32:33], v[0:1], off offset:32 sc1
	v_cvt_pk_bf16_f32 v0, v12, v13
	v_cvt_pk_bf16_f32 v1, v14, v15
	global_store_dwordx2 v[32:33], v[0:1], off offset:48 sc1
	v_cvt_pk_bf16_f32 v0, v16, v17
	v_cvt_pk_bf16_f32 v1, v18, v19
	global_store_dwordx2 v[32:33], v[0:1], off offset:64 sc1
	v_cvt_pk_bf16_f32 v0, v20, v21
	v_cvt_pk_bf16_f32 v1, v22, v23
	global_store_dwordx2 v[32:33], v[0:1], off offset:80 sc1
	v_cvt_pk_bf16_f32 v0, v24, v25
	v_cvt_pk_bf16_f32 v1, v26, v27
	global_store_dwordx2 v[32:33], v[0:1], off offset:96 sc1
	v_cvt_pk_bf16_f32 v0, v28, v29
	v_cvt_pk_bf16_f32 v1, v30, v31
	s_movk_i32 s39, 0x80
.LBB0_263:
	s_andn2_saveexec_b64 s[0:1], s[56:57]
	s_cbranch_execz .LBB0_242
	v_mov_b32_e32 v41, v65
	s_mov_b32 s66, s67
	v_lshl_add_u64 v[0:1], v[88:89], 0, v[40:41]
	v_mov_b64_e32 v[2:3], s[66:67]
	global_store_dwordx2 v[0:1], v[2:3], off sc1
	global_store_dwordx2 v[0:1], v[2:3], off offset:16 sc1
	global_store_dwordx2 v[0:1], v[2:3], off offset:32 sc1
	global_store_dwordx2 v[0:1], v[2:3], off offset:48 sc1
	global_store_dwordx2 v[0:1], v[2:3], off offset:64 sc1
	global_store_dwordx2 v[0:1], v[2:3], off offset:80 sc1
	global_store_dwordx2 v[0:1], v[2:3], off offset:96 sc1
	v_mov_b32_e32 v0, 0
	v_mov_b32_e32 v91, v65
	v_mov_b32_e32 v1, v0
	s_branch .LBB0_242

;     DEVINL bf16_t* Z() const { return (bf16_t*)(ws + OFF_Z); }
;     DEVINL bf16_t* Y() const { return (bf16_t*)(ws + OFF_Y); }
; DEVINL unsigned cvt_pk_bf16(float lo, float hi) { const f32x2 v = {lo, hi}; return __builtin_bit_cast(unsigned, __builtin_convertvector(v, bf16x2v)); }
; DEVINL float bflo(unsigned u) { return __uint_as_float(u << 16); }
; DEVINL float bfhi(unsigned u) { return __uint_as_float(u & 0xffff0000u); }
; DEVINL float sigmoidf_(float x) { return __builtin_amdgcn_rcpf(1.f + fexp2(-x * LOG2E)); }
; DEVINL void ret_block(const Ctx& c, int b, int hd, unsigned char* lds) {
;     ...
;         const float rs = rsqrtf((ssq[ql] + ssq[128 + ql]) * (1.f / 128.f) + 1e-6f);
;         {
;             const bf16_t* gp = c.Z() + (size_t)(t0 + ql) * ZW + Z_BG + hd * 128 + dh * 64;
;             bf16_t* yp = Y + (size_t)(t0 + ql) * 512 + hd * 128 + dh * 64;
; #pragma unroll
;             for (int d = 0; d < 2; ++d)
; #pragma unroll
;                 for (int g = 0; g < 4; ++g) {
;                     const int dl = d * 32 + 8 * g + 4 * h;
;                     const u32x2 gg = *(const u32x2*)(gp + dl);
;                     float gv[4] = {bflo(gg[0]), bfhi(gg[0]), bflo(gg[1]), bfhi(gg[1])};
;                     float ov[4];
; #pragma unroll
;                     for (int j = 0; j < 4; ++j) { const float sg = gv[j] * sigmoidf_(gv[j]); ov[j] = sg * o[d][4 * g + j] * rs; }
;                     u32x2 pk; pk[0] = cvt_pk_bf16(ov[0], ov[1]); pk[1] = cvt_pk_bf16(ov[2], ov[3]);
;                     *(u32x2*)(yp + dl) = pk;
;                 }
;         }
; #pragma unroll
;         for (int i = 0; i < 16; ++i) sacc[i] *= gam128;
.LBB0_272:
	s_or_b64 exec, exec, s[4:5]
	s_waitcnt lgkmcnt(0)
	s_barrier
	ds_read2st64_b32 v[18:19], v123 offset0:72 offset1:74
	s_mov_b32 s4, 0x800000
	v_lshlrev_b64 v[28:29], 10, v[64:65]
	v_lshlrev_b32_e32 v64, 1, v90
	v_mov_b32_e32 v89, v88
	s_waitcnt lgkmcnt(0)
	v_add_f32_e32 v18, v18, v19
	v_fmamk_f32 v18, v18, 0x3c000000, v161
	v_cmp_gt_f32_e32 vcc, s4, v18
	v_mul_f32_e32 v19, 0x4b800000, v18
	v_readlane_b32 s4, v246, 27
	v_cndmask_b32_e32 v18, v18, v19, vcc
	v_readlane_b32 s5, v246, 28
	v_rsq_f32_e32 v18, v18
	v_pk_mul_f32 v[14:15], v[88:89], v[14:15]
	v_lshl_add_u64 v[22:23], v[116:117], 1, s[4:5]
	v_lshl_add_u64 v[22:23], v[22:23], 0, s[66:67]
	v_lshl_add_u64 v[22:23], v[94:95], 1, v[22:23]
	v_lshl_add_u64 v[22:23], v[22:23], 0, v[64:65]
	s_mov_b64 s[4:5], 0x2940c00
	v_mul_f32_e32 v19, 0x45800000, v18
	v_lshl_add_u64 v[24:25], v[22:23], 0, s[4:5]
	s_mov_b32 s4, 0x2940000
	v_cndmask_b32_e32 v18, v18, v19, vcc
	v_add_co_u32_e32 v22, vcc, s4, v22
	s_mov_b32 s4, 0
	s_nop 0
	v_addc_co_u32_e32 v23, vcc, 0, v23, vcc
	v_mov_b64_e32 v[22:23], v[186:187]
	v_pk_mul_f32 v[12:13], v[88:89], v[12:13]
	v_pk_mul_f32 v[10:11], v[88:89], v[10:11]
	v_pk_mul_f32 v[8:9], v[88:89], v[8:9]
	v_pk_mul_f32 v[6:7], v[88:89], v[6:7]
	v_pk_mul_f32 v[4:5], v[88:89], v[4:5]
	v_pk_mul_f32 v[2:3], v[88:89], v[2:3]
	v_pk_mul_f32 v[0:1], v[102:103], v[0:1]
	v_lshlrev_b32_e32 v30, 16, v22
	v_mul_f32_e32 v19, 0xbfb8aa3b, v30
	v_exp_f32_e32 v19, v19
	v_and_b32_e32 v31, 0xffff0000, v22
	v_lshlrev_b32_e32 v22, 16, v23
	v_and_b32_e32 v23, 0xffff0000, v23
	v_add_f32_e32 v19, 1.0, v19
	v_rcp_f32_e32 v46, v19
	v_mul_f32_e32 v19, 0xbfb8aa3b, v31
	v_exp_f32_e32 v19, v19
	s_nop 0
	v_add_f32_e32 v19, 1.0, v19
	v_rcp_f32_e32 v47, v19
	s_nop 0
	v_pk_mul_f32 v[30:31], v[46:47], v[30:31]
	s_nop 0
	v_pk_mul_f32 v[30:31], v[58:59], v[30:31]
	s_nop 0
	v_pk_mul_f32 v[30:31], v[18:19], v[30:31] op_sel_hi:[0,1]
	v_mul_f32_e32 v19, 0xbfb8aa3b, v22
	v_exp_f32_e32 v19, v19
	v_cvt_pk_bf16_f32 v30, v30, v31
	v_add_f32_e32 v19, 1.0, v19
	v_rcp_f32_e32 v46, v19
	v_mul_f32_e32 v19, 0xbfb8aa3b, v23
	v_exp_f32_e32 v19, v19
	s_nop 0
	v_add_f32_e32 v19, 1.0, v19
	v_rcp_f32_e32 v47, v19
	s_nop 0
	v_pk_mul_f32 v[22:23], v[46:47], v[22:23]
	s_nop 0
	v_pk_mul_f32 v[22:23], v[56:57], v[22:23]
	s_nop 0
	v_pk_mul_f32 v[22:23], v[18:19], v[22:23] op_sel_hi:[0,1]
	v_cvt_pk_bf16_f32 v31, v22, v23
	v_lshl_add_u64 v[22:23], v[106:107], 0, v[28:29]
	v_mov_b64_e32 v[28:29], v[188:189]
	s_nop 0
	global_store_dwordx2 v[22:23], v[30:31], off sc1
	v_lshlrev_b32_e32 v30, 16, v28
	v_mul_f32_e32 v19, 0xbfb8aa3b, v30
	v_exp_f32_e32 v19, v19
	v_and_b32_e32 v31, 0xffff0000, v28
	v_lshlrev_b32_e32 v28, 16, v29
	v_and_b32_e32 v29, 0xffff0000, v29
	v_add_f32_e32 v19, 1.0, v19
	v_rcp_f32_e32 v46, v19
	v_mul_f32_e32 v19, 0xbfb8aa3b, v31
	v_exp_f32_e32 v19, v19
	s_nop 0
	v_add_f32_e32 v19, 1.0, v19
	v_rcp_f32_e32 v47, v19
	s_nop 0
	v_pk_mul_f32 v[30:31], v[46:47], v[30:31]
	s_nop 0
	v_pk_mul_f32 v[30:31], v[54:55], v[30:31]
	s_nop 0
	v_pk_mul_f32 v[30:31], v[18:19], v[30:31] op_sel_hi:[0,1]
	v_mul_f32_e32 v19, 0xbfb8aa3b, v28
	v_exp_f32_e32 v19, v19
	v_cvt_pk_bf16_f32 v30, v30, v31
	v_add_f32_e32 v19, 1.0, v19
	v_rcp_f32_e32 v46, v19
	v_mul_f32_e32 v19, 0xbfb8aa3b, v29
	v_exp_f32_e32 v19, v19
	s_nop 0
	v_add_f32_e32 v19, 1.0, v19
	v_rcp_f32_e32 v47, v19
	s_nop 0
	v_pk_mul_f32 v[28:29], v[46:47], v[28:29]
	s_nop 0
	v_pk_mul_f32 v[28:29], v[52:53], v[28:29]
	s_nop 0
	v_pk_mul_f32 v[28:29], v[18:19], v[28:29] op_sel_hi:[0,1]
	v_cvt_pk_bf16_f32 v31, v28, v29
	v_mov_b64_e32 v[28:29], v[190:191]
	s_nop 0
	global_store_dwordx2 v[22:23], v[30:31], off offset:16 sc1
	v_lshlrev_b32_e32 v30, 16, v28
	v_mul_f32_e32 v19, 0xbfb8aa3b, v30
	v_exp_f32_e32 v19, v19
	v_and_b32_e32 v31, 0xffff0000, v28
	v_lshlrev_b32_e32 v28, 16, v29
	v_and_b32_e32 v29, 0xffff0000, v29
	v_add_f32_e32 v19, 1.0, v19
	v_rcp_f32_e32 v46, v19
	v_mul_f32_e32 v19, 0xbfb8aa3b, v31
	v_exp_f32_e32 v19, v19
	s_nop 0
	v_add_f32_e32 v19, 1.0, v19
	v_rcp_f32_e32 v47, v19
	s_nop 0
	v_pk_mul_f32 v[30:31], v[46:47], v[30:31]
	s_nop 0
	v_pk_mul_f32 v[30:31], v[50:51], v[30:31]
	s_nop 0
	v_pk_mul_f32 v[30:31], v[18:19], v[30:31] op_sel_hi:[0,1]
	v_mul_f32_e32 v19, 0xbfb8aa3b, v28
	v_exp_f32_e32 v19, v19
	v_cvt_pk_bf16_f32 v30, v30, v31
	v_add_f32_e32 v19, 1.0, v19
	v_rcp_f32_e32 v46, v19
	v_mul_f32_e32 v19, 0xbfb8aa3b, v29
	v_exp_f32_e32 v19, v19
	s_nop 0
	v_add_f32_e32 v19, 1.0, v19
	v_rcp_f32_e32 v47, v19
	s_nop 0
	v_pk_mul_f32 v[28:29], v[46:47], v[28:29]
	s_nop 0
	v_pk_mul_f32 v[28:29], v[48:49], v[28:29]
	s_nop 0
	v_pk_mul_f32 v[28:29], v[18:19], v[28:29] op_sel_hi:[0,1]
	v_cvt_pk_bf16_f32 v31, v28, v29
	v_mov_b64_e32 v[28:29], v[192:193]
	s_nop 0
	global_store_dwordx2 v[22:23], v[30:31], off offset:32 sc1
	v_lshlrev_b32_e32 v30, 16, v28
	v_mul_f32_e32 v19, 0xbfb8aa3b, v30
	v_exp_f32_e32 v19, v19
	v_and_b32_e32 v31, 0xffff0000, v28
	v_lshlrev_b32_e32 v28, 16, v29
	v_and_b32_e32 v29, 0xffff0000, v29
	v_add_f32_e32 v19, 1.0, v19
	v_rcp_f32_e32 v46, v19
	v_mul_f32_e32 v19, 0xbfb8aa3b, v31
	v_exp_f32_e32 v19, v19
	s_nop 0
	v_add_f32_e32 v19, 1.0, v19
	v_rcp_f32_e32 v47, v19
	s_nop 0
	v_pk_mul_f32 v[30:31], v[46:47], v[30:31]
	s_nop 0
	v_pk_mul_f32 v[30:31], v[44:45], v[30:31]
	s_nop 0
	v_pk_mul_f32 v[30:31], v[18:19], v[30:31] op_sel_hi:[0,1]
	v_mul_f32_e32 v19, 0xbfb8aa3b, v28
	v_exp_f32_e32 v19, v19
	v_cvt_pk_bf16_f32 v30, v30, v31
	v_add_f32_e32 v19, 1.0, v19
	v_rcp_f32_e32 v44, v19
	v_mul_f32_e32 v19, 0xbfb8aa3b, v29
	v_exp_f32_e32 v19, v19
	s_nop 0
	v_add_f32_e32 v19, 1.0, v19
	v_rcp_f32_e32 v45, v19
	s_nop 0
	v_pk_mul_f32 v[28:29], v[44:45], v[28:29]
	s_nop 0
; #define MFMA32(a, b, c) __builtin_amdgcn_mfma_f32_32x32x16_bf16((a), (b), (c), 0, 0, 0)
; DEVINL unsigned cvt_pk_bf16(float lo, float hi) { const f32x2 v = {lo, hi}; return __builtin_bit_cast(unsigned, __builtin_convertvector(v, bf16x2v)); }
; DEVINL float bflo(unsigned u) { return __uint_as_float(u << 16); }
; DEVINL float bfhi(unsigned u) { return __uint_as_float(u & 0xffff0000u); }
; DEVINL float fexp2(float x) { return __builtin_amdgcn_exp2f(x); }
; DEVINL float sigmoidf_(float x) { return __builtin_amdgcn_rcpf(1.f + fexp2(-x * LOG2E)); }
; DEVINL void ret_block(const Ctx& c, int b, int hd, unsigned char* lds) {
;     ...
;                     const int dl = d * 32 + 8 * g + 4 * h;
;                     const u32x2 gg = *(const u32x2*)(gp + dl);
;                     float gv[4] = {bflo(gg[0]), bfhi(gg[0]), bflo(gg[1]), bfhi(gg[1])};
;                     float ov[4];
; #pragma unroll
;                     for (int j = 0; j < 4; ++j) { const float sg = gv[j] * sigmoidf_(gv[j]); ov[j] = sg * o[d][4 * g + j] * rs; }
;                     u32x2 pk; pk[0] = cvt_pk_bf16(ov[0], ov[1]); pk[1] = cvt_pk_bf16(ov[2], ov[3]);
;                     *(u32x2*)(yp + dl) = pk;
;                 }
;         }
; #pragma unroll
;         for (int i = 0; i < 16; ++i) sacc[i] *= gam128;
;         {
;             const bf16_t* va = vtb + (size_t)(dvt * 32 + r) * L + p0 + 8 * h;
;             const bf16_t* kb = ktb + (size_t)(dt * 32 + r) * L + p0 + 8 * h;
; #pragma unroll 2
;             for (int ks = 0; ks < 8; ++ks) {
;                 const bf16x8 vf = *(const bf16x8*)(va + 16 * ks);
;                 const u32x4 kr = *(const u32x4*)(kb + 16 * ks);
;                 u32x4 kd;
; #pragma unroll
;                 for (int jj = 0; jj < 4; ++jj) {
;                     const int j0 = 16 * ks + 8 * h + 2 * jj;
;                     kd[jj] = cvt_pk_bf16(bflo(kr[jj]) * fexp2(lg2 * (float)(127 - j0)), bfhi(kr[jj]) * fexp2(lg2 * (float)(126 - j0)));
;                 }
;                 sacc = MFMA32(vf, __builtin_bit_cast(bf16x8, kd), sacc);
	v_pk_mul_f32 v[28:29], v[42:43], v[28:29]
	s_nop 0
	v_pk_mul_f32 v[28:29], v[18:19], v[28:29] op_sel_hi:[0,1]
	v_cvt_pk_bf16_f32 v31, v28, v29
	v_mov_b64_e32 v[28:29], v[194:195]
	s_nop 0
	global_store_dwordx2 v[22:23], v[30:31], off offset:48 sc1
	v_lshlrev_b32_e32 v30, 16, v28
	v_mul_f32_e32 v19, 0xbfb8aa3b, v30
	v_exp_f32_e32 v19, v19
	v_and_b32_e32 v31, 0xffff0000, v28
	v_lshlrev_b32_e32 v28, 16, v29
	v_and_b32_e32 v29, 0xffff0000, v29
	v_add_f32_e32 v19, 1.0, v19
	v_rcp_f32_e32 v42, v19
	v_mul_f32_e32 v19, 0xbfb8aa3b, v31
	v_exp_f32_e32 v19, v19
	s_nop 0
	v_add_f32_e32 v19, 1.0, v19
	v_rcp_f32_e32 v43, v19
	s_nop 0
	v_pk_mul_f32 v[30:31], v[42:43], v[30:31]
	s_nop 0
	v_pk_mul_f32 v[30:31], v[40:41], v[30:31]
	s_nop 0
	v_pk_mul_f32 v[30:31], v[18:19], v[30:31] op_sel_hi:[0,1]
	v_mul_f32_e32 v19, 0xbfb8aa3b, v28
	v_exp_f32_e32 v19, v19
	v_cvt_pk_bf16_f32 v30, v30, v31
	v_add_f32_e32 v19, 1.0, v19
	v_rcp_f32_e32 v40, v19
	v_mul_f32_e32 v19, 0xbfb8aa3b, v29
	v_exp_f32_e32 v19, v19
	s_nop 0
	v_add_f32_e32 v19, 1.0, v19
	v_rcp_f32_e32 v41, v19
	s_nop 0
	v_pk_mul_f32 v[28:29], v[40:41], v[28:29]
	s_nop 0
	v_pk_mul_f32 v[28:29], v[38:39], v[28:29]
	s_nop 0
	v_pk_mul_f32 v[28:29], v[18:19], v[28:29] op_sel_hi:[0,1]
	v_cvt_pk_bf16_f32 v31, v28, v29
	v_mov_b64_e32 v[28:29], v[196:197]
	s_nop 0
	global_store_dwordx2 v[22:23], v[30:31], off offset:64 sc1
	v_lshlrev_b32_e32 v30, 16, v28
	v_mul_f32_e32 v19, 0xbfb8aa3b, v30
	v_exp_f32_e32 v19, v19
	v_and_b32_e32 v31, 0xffff0000, v28
	v_lshlrev_b32_e32 v28, 16, v29
	v_and_b32_e32 v29, 0xffff0000, v29
	v_add_f32_e32 v19, 1.0, v19
	v_rcp_f32_e32 v38, v19
	v_mul_f32_e32 v19, 0xbfb8aa3b, v31
	v_exp_f32_e32 v19, v19
	s_nop 0
	v_add_f32_e32 v19, 1.0, v19
	v_rcp_f32_e32 v39, v19
	s_nop 0
	v_pk_mul_f32 v[30:31], v[38:39], v[30:31]
	s_nop 0
	v_pk_mul_f32 v[30:31], v[36:37], v[30:31]
	s_nop 0
	v_pk_mul_f32 v[30:31], v[18:19], v[30:31] op_sel_hi:[0,1]
	v_mul_f32_e32 v19, 0xbfb8aa3b, v28
	v_exp_f32_e32 v19, v19
	v_cvt_pk_bf16_f32 v30, v30, v31
	v_add_f32_e32 v19, 1.0, v19
	v_rcp_f32_e32 v36, v19
	v_mul_f32_e32 v19, 0xbfb8aa3b, v29
	v_exp_f32_e32 v19, v19
	s_nop 0
	v_add_f32_e32 v19, 1.0, v19
	v_rcp_f32_e32 v37, v19
	s_nop 0
	v_pk_mul_f32 v[28:29], v[36:37], v[28:29]
	s_nop 0
	v_pk_mul_f32 v[28:29], v[34:35], v[28:29]
	s_nop 0
	v_pk_mul_f32 v[28:29], v[18:19], v[28:29] op_sel_hi:[0,1]
	v_cvt_pk_bf16_f32 v31, v28, v29
	v_mov_b64_e32 v[28:29], v[198:199]
	s_nop 0
	v_mov_b64_e32 v[24:25], v[200:201]
	s_nop 0
	global_store_dwordx2 v[22:23], v[30:31], off offset:80 sc1
	v_lshlrev_b32_e32 v30, 16, v28
	v_mul_f32_e32 v19, 0xbfb8aa3b, v30
	v_exp_f32_e32 v19, v19
	v_and_b32_e32 v31, 0xffff0000, v28
	v_lshlrev_b32_e32 v28, 16, v29
	v_and_b32_e32 v29, 0xffff0000, v29
	v_add_f32_e32 v19, 1.0, v19
	v_rcp_f32_e32 v34, v19
	v_mul_f32_e32 v19, 0xbfb8aa3b, v31
	v_exp_f32_e32 v19, v19
	s_nop 0
	v_add_f32_e32 v19, 1.0, v19
	v_rcp_f32_e32 v35, v19
	s_nop 0
	v_pk_mul_f32 v[30:31], v[34:35], v[30:31]
	s_nop 0
	v_pk_mul_f32 v[30:31], v[32:33], v[30:31]
	s_nop 0
	v_pk_mul_f32 v[30:31], v[18:19], v[30:31] op_sel_hi:[0,1]
	v_mul_f32_e32 v19, 0xbfb8aa3b, v28
	v_exp_f32_e32 v19, v19
	s_nop 0
	v_add_f32_e32 v19, 1.0, v19
	v_rcp_f32_e32 v32, v19
	v_mul_f32_e32 v19, 0xbfb8aa3b, v29
	v_exp_f32_e32 v19, v19
	s_nop 0
	v_add_f32_e32 v19, 1.0, v19
	v_rcp_f32_e32 v33, v19
	s_nop 0
	v_pk_mul_f32 v[28:29], v[32:33], v[28:29]
	s_nop 0
	v_pk_mul_f32 v[26:27], v[26:27], v[28:29]
	v_cvt_pk_bf16_f32 v28, v30, v31
	v_pk_mul_f32 v[26:27], v[18:19], v[26:27] op_sel_hi:[0,1]
	v_cvt_pk_bf16_f32 v29, v26, v27
	v_lshlrev_b32_e32 v26, 16, v24
	v_mul_f32_e32 v19, 0xbfb8aa3b, v26
	v_exp_f32_e32 v19, v19
	v_and_b32_e32 v27, 0xffff0000, v24
	global_store_dwordx2 v[22:23], v[28:29], off offset:96 sc1
	v_lshlrev_b32_e32 v24, 16, v25
	v_add_f32_e32 v19, 1.0, v19
	v_rcp_f32_e32 v28, v19
	v_mul_f32_e32 v19, 0xbfb8aa3b, v27
	v_exp_f32_e32 v19, v19
	v_and_b32_e32 v25, 0xffff0000, v25
	v_add_f32_e32 v19, 1.0, v19
	v_rcp_f32_e32 v29, v19
	s_nop 0
	v_pk_mul_f32 v[26:27], v[28:29], v[26:27]
	s_nop 0
	v_pk_mul_f32 v[20:21], v[20:21], v[26:27]
	s_nop 0
	v_pk_mul_f32 v[20:21], v[18:19], v[20:21] op_sel_hi:[0,1]
	v_mul_f32_e32 v19, 0xbfb8aa3b, v24
	v_exp_f32_e32 v19, v19
	s_nop 0
	v_add_f32_e32 v19, 1.0, v19
	v_rcp_f32_e32 v26, v19
	v_mul_f32_e32 v19, 0xbfb8aa3b, v25
	v_exp_f32_e32 v19, v19
	s_nop 0
	v_add_f32_e32 v19, 1.0, v19
	v_rcp_f32_e32 v27, v19
	s_nop 0
	v_pk_mul_f32 v[24:25], v[26:27], v[24:25]
	s_nop 0
	v_pk_mul_f32 v[16:17], v[16:17], v[24:25]
	v_mov_b64_e32 v[24:25], v[114:115]
	v_pk_mul_f32 v[16:17], v[18:19], v[16:17] op_sel_hi:[0,1]
	v_cvt_pk_bf16_f32 v18, v20, v21
	v_cvt_pk_bf16_f32 v19, v16, v17
	v_mov_b64_e32 v[26:27], v[112:113]
	global_store_dwordx2 v[22:23], v[18:19], off offset:112 sc1
	s_waitcnt vmcnt(22)
	v_add_u32_e32 v32, 127, v126
	v_add_u32_e32 v33, 126, v126
	v_cvt_f32_u32_e32 v32, v32
	v_cvt_f32_u32_e32 v33, v33
	v_lshlrev_b32_e32 v34, 16, v136
	v_and_b32_e32 v35, 0xffff0000, v136
	v_mul_f32_e32 v32, v93, v32
	v_mul_f32_e32 v33, v93, v33
	v_exp_f32_e32 v32, v32
	v_exp_f32_e32 v33, v33
	s_nop 0
	v_pk_mul_f32 v[32:33], v[32:33], v[34:35]
	s_nop 0
	v_cvt_pk_bf16_f32 v136, v32, v33
	v_add_u32_e32 v32, 125, v126
	v_add_u32_e32 v33, 124, v126
	v_cvt_f32_u32_e32 v32, v32
	v_cvt_f32_u32_e32 v33, v33
	v_lshlrev_b32_e32 v34, 16, v137
	v_and_b32_e32 v35, 0xffff0000, v137
	v_mul_f32_e32 v32, v93, v32
	v_mul_f32_e32 v33, v93, v33
	v_exp_f32_e32 v32, v32
	v_exp_f32_e32 v33, v33
	s_nop 0
	v_pk_mul_f32 v[32:33], v[32:33], v[34:35]
	s_nop 0
	v_cvt_pk_bf16_f32 v137, v32, v33
	v_add_u32_e32 v32, 123, v126
	v_add_u32_e32 v33, 122, v126
	v_cvt_f32_u32_e32 v32, v32
	v_cvt_f32_u32_e32 v33, v33
	v_lshlrev_b32_e32 v34, 16, v138
	v_and_b32_e32 v35, 0xffff0000, v138
	v_mul_f32_e32 v32, v93, v32
	v_mul_f32_e32 v33, v93, v33
	v_exp_f32_e32 v32, v32
	v_exp_f32_e32 v33, v33
	s_nop 0
	v_pk_mul_f32 v[32:33], v[32:33], v[34:35]
	s_nop 0
	v_cvt_pk_bf16_f32 v138, v32, v33
	v_add_u32_e32 v32, 121, v126
	v_add_u32_e32 v33, 120, v126
	v_cvt_f32_u32_e32 v32, v32
	v_cvt_f32_u32_e32 v33, v33
	v_lshlrev_b32_e32 v34, 16, v139
	v_and_b32_e32 v35, 0xffff0000, v139
	v_mul_f32_e32 v32, v93, v32
	v_mul_f32_e32 v33, v93, v33
	v_exp_f32_e32 v32, v32
	v_exp_f32_e32 v33, v33
	s_nop 0
	v_pk_mul_f32 v[32:33], v[32:33], v[34:35]
	s_nop 0
	v_cvt_pk_bf16_f32 v139, v32, v33
	s_nop 1
	v_mfma_f32_32x32x16_bf16 v[0:15], v[132:135], v[136:139], v[0:15]
	s_waitcnt vmcnt(20)
; #define MFMA32(a, b, c) __builtin_amdgcn_mfma_f32_32x32x16_bf16((a), (b), (c), 0, 0, 0)
; DEVINL unsigned cvt_pk_bf16(float lo, float hi) { const f32x2 v = {lo, hi}; return __builtin_bit_cast(unsigned, __builtin_convertvector(v, bf16x2v)); }
; DEVINL float bflo(unsigned u) { return __uint_as_float(u << 16); }
; DEVINL float bfhi(unsigned u) { return __uint_as_float(u & 0xffff0000u); }
; DEVINL float fexp2(float x) { return __builtin_amdgcn_exp2f(x); }
; DEVINL void ret_block(const Ctx& c, int b, int hd, unsigned char* lds) {
;     ...
;             for (int ks = 0; ks < 8; ++ks) {
;                 const bf16x8 vf = *(const bf16x8*)(va + 16 * ks);
;                 const u32x4 kr = *(const u32x4*)(kb + 16 * ks);
;                 u32x4 kd;
; #pragma unroll
;                 for (int jj = 0; jj < 4; ++jj) {
;                     const int j0 = 16 * ks + 8 * h + 2 * jj;
;                     kd[jj] = cvt_pk_bf16(bflo(kr[jj]) * fexp2(lg2 * (float)(127 - j0)), bfhi(kr[jj]) * fexp2(lg2 * (float)(126 - j0)));
;                 }
;                 sacc = MFMA32(vf, __builtin_bit_cast(bf16x8, kd), sacc);
	v_add_u32_e32 v32, 111, v126
	v_add_u32_e32 v33, 110, v126
	v_cvt_f32_u32_e32 v32, v32
	v_cvt_f32_u32_e32 v33, v33
	v_lshlrev_b32_e32 v34, 16, v144
	v_and_b32_e32 v35, 0xffff0000, v144
	v_mul_f32_e32 v32, v93, v32
	v_mul_f32_e32 v33, v93, v33
	v_exp_f32_e32 v32, v32
	v_exp_f32_e32 v33, v33
	s_nop 0
	v_pk_mul_f32 v[32:33], v[32:33], v[34:35]
	s_nop 0
	v_cvt_pk_bf16_f32 v144, v32, v33
	v_add_u32_e32 v32, 109, v126
	v_add_u32_e32 v33, 108, v126
	v_cvt_f32_u32_e32 v32, v32
	v_cvt_f32_u32_e32 v33, v33
	v_lshlrev_b32_e32 v34, 16, v145
	v_and_b32_e32 v35, 0xffff0000, v145
	v_mul_f32_e32 v32, v93, v32
	v_mul_f32_e32 v33, v93, v33
	v_exp_f32_e32 v32, v32
	v_exp_f32_e32 v33, v33
	s_nop 0
	v_pk_mul_f32 v[32:33], v[32:33], v[34:35]
	s_nop 0
	v_cvt_pk_bf16_f32 v145, v32, v33
	v_add_u32_e32 v32, 107, v126
	v_add_u32_e32 v33, 106, v126
	v_cvt_f32_u32_e32 v32, v32
	v_cvt_f32_u32_e32 v33, v33
	v_lshlrev_b32_e32 v34, 16, v146
	v_and_b32_e32 v35, 0xffff0000, v146
	v_mul_f32_e32 v32, v93, v32
	v_mul_f32_e32 v33, v93, v33
	v_exp_f32_e32 v32, v32
	v_exp_f32_e32 v33, v33
	s_nop 0
	v_pk_mul_f32 v[32:33], v[32:33], v[34:35]
	s_nop 0
	v_cvt_pk_bf16_f32 v146, v32, v33
	v_add_u32_e32 v32, 105, v126
	v_add_u32_e32 v33, 104, v126
	v_cvt_f32_u32_e32 v32, v32
	v_cvt_f32_u32_e32 v33, v33
	v_lshlrev_b32_e32 v34, 16, v147
	v_and_b32_e32 v35, 0xffff0000, v147
	v_mul_f32_e32 v32, v93, v32
	v_mul_f32_e32 v33, v93, v33
	v_exp_f32_e32 v32, v32
	v_exp_f32_e32 v33, v33
	s_nop 0
	v_pk_mul_f32 v[32:33], v[32:33], v[34:35]
	s_nop 0
	v_cvt_pk_bf16_f32 v147, v32, v33
	s_nop 1
	v_mfma_f32_32x32x16_bf16 v[0:15], v[140:143], v[144:147], v[0:15]
	s_waitcnt vmcnt(18)
	v_add_u32_e32 v32, 95, v126
	v_add_u32_e32 v33, 94, v126
	v_cvt_f32_u32_e32 v32, v32
	v_cvt_f32_u32_e32 v33, v33
	v_lshlrev_b32_e32 v34, 16, v152
	v_and_b32_e32 v35, 0xffff0000, v152
	v_mul_f32_e32 v32, v93, v32
	v_mul_f32_e32 v33, v93, v33
	v_exp_f32_e32 v32, v32
	v_exp_f32_e32 v33, v33
	s_nop 0
	v_pk_mul_f32 v[32:33], v[32:33], v[34:35]
	s_nop 0
	v_cvt_pk_bf16_f32 v152, v32, v33
	v_add_u32_e32 v32, 93, v126
	v_add_u32_e32 v33, 92, v126
	v_cvt_f32_u32_e32 v32, v32
	v_cvt_f32_u32_e32 v33, v33
	v_lshlrev_b32_e32 v34, 16, v153
	v_and_b32_e32 v35, 0xffff0000, v153
	v_mul_f32_e32 v32, v93, v32
	v_mul_f32_e32 v33, v93, v33
	v_exp_f32_e32 v32, v32
	v_exp_f32_e32 v33, v33
	s_nop 0
	v_pk_mul_f32 v[32:33], v[32:33], v[34:35]
	s_nop 0
	v_cvt_pk_bf16_f32 v153, v32, v33
	v_add_u32_e32 v32, 91, v126
	v_add_u32_e32 v33, 90, v126
	v_cvt_f32_u32_e32 v32, v32
	v_cvt_f32_u32_e32 v33, v33
	v_lshlrev_b32_e32 v34, 16, v154
	v_and_b32_e32 v35, 0xffff0000, v154
	v_mul_f32_e32 v32, v93, v32
	v_mul_f32_e32 v33, v93, v33
	v_exp_f32_e32 v32, v32
	v_exp_f32_e32 v33, v33
	s_nop 0
	v_pk_mul_f32 v[32:33], v[32:33], v[34:35]
	s_nop 0
	v_cvt_pk_bf16_f32 v154, v32, v33
	v_add_u32_e32 v32, 89, v126
	v_add_u32_e32 v33, 88, v126
	v_cvt_f32_u32_e32 v32, v32
	v_cvt_f32_u32_e32 v33, v33
	v_lshlrev_b32_e32 v34, 16, v155
	v_and_b32_e32 v35, 0xffff0000, v155
	v_mul_f32_e32 v32, v93, v32
	v_mul_f32_e32 v33, v93, v33
	v_exp_f32_e32 v32, v32
	v_exp_f32_e32 v33, v33
	s_nop 0
	v_pk_mul_f32 v[32:33], v[32:33], v[34:35]
	s_nop 0
	v_cvt_pk_bf16_f32 v155, v32, v33
	s_nop 1
	v_mfma_f32_32x32x16_bf16 v[0:15], v[148:151], v[152:155], v[0:15]
	s_waitcnt vmcnt(16)
	v_add_u32_e32 v32, 79, v126
	v_add_u32_e32 v33, 78, v126
	v_cvt_f32_u32_e32 v32, v32
	v_cvt_f32_u32_e32 v33, v33
	v_lshlrev_b32_e32 v34, 16, v168
	v_and_b32_e32 v35, 0xffff0000, v168
	v_mul_f32_e32 v32, v93, v32
	v_mul_f32_e32 v33, v93, v33
	v_exp_f32_e32 v32, v32
	v_exp_f32_e32 v33, v33
	s_nop 0
	v_pk_mul_f32 v[32:33], v[32:33], v[34:35]
	s_nop 0
	v_cvt_pk_bf16_f32 v168, v32, v33
	v_add_u32_e32 v32, 77, v126
	v_add_u32_e32 v33, 76, v126
	v_cvt_f32_u32_e32 v32, v32
	v_cvt_f32_u32_e32 v33, v33
	v_lshlrev_b32_e32 v34, 16, v169
	v_and_b32_e32 v35, 0xffff0000, v169
	v_mul_f32_e32 v32, v93, v32
	v_mul_f32_e32 v33, v93, v33
	v_exp_f32_e32 v32, v32
	v_exp_f32_e32 v33, v33
	s_nop 0
	v_pk_mul_f32 v[32:33], v[32:33], v[34:35]
	s_nop 0
	v_cvt_pk_bf16_f32 v169, v32, v33
	v_add_u32_e32 v32, 75, v126
	v_add_u32_e32 v33, 74, v126
	v_cvt_f32_u32_e32 v32, v32
	v_cvt_f32_u32_e32 v33, v33
	v_lshlrev_b32_e32 v34, 16, v170
	v_and_b32_e32 v35, 0xffff0000, v170
	v_mul_f32_e32 v32, v93, v32
	v_mul_f32_e32 v33, v93, v33
	v_exp_f32_e32 v32, v32
	v_exp_f32_e32 v33, v33
	s_nop 0
	v_pk_mul_f32 v[32:33], v[32:33], v[34:35]
	s_nop 0
	v_cvt_pk_bf16_f32 v170, v32, v33
	v_add_u32_e32 v32, 73, v126
	v_add_u32_e32 v33, 72, v126
	v_cvt_f32_u32_e32 v32, v32
	v_cvt_f32_u32_e32 v33, v33
	v_lshlrev_b32_e32 v34, 16, v171
	v_and_b32_e32 v35, 0xffff0000, v171
	v_mul_f32_e32 v32, v93, v32
	v_mul_f32_e32 v33, v93, v33
	v_exp_f32_e32 v32, v32
	v_exp_f32_e32 v33, v33
	s_nop 0
	v_pk_mul_f32 v[32:33], v[32:33], v[34:35]
	s_nop 0
	v_cvt_pk_bf16_f32 v171, v32, v33
	s_nop 1
	v_mfma_f32_32x32x16_bf16 v[0:15], v[156:159], v[168:171], v[0:15]
	s_waitcnt vmcnt(14)
; #define MFMA32(a, b, c) __builtin_amdgcn_mfma_f32_32x32x16_bf16((a), (b), (c), 0, 0, 0)
; DEVINL unsigned cvt_pk_bf16(float lo, float hi) { const f32x2 v = {lo, hi}; return __builtin_bit_cast(unsigned, __builtin_convertvector(v, bf16x2v)); }
; DEVINL float bflo(unsigned u) { return __uint_as_float(u << 16); }
; DEVINL float bfhi(unsigned u) { return __uint_as_float(u & 0xffff0000u); }
; DEVINL float fexp2(float x) { return __builtin_amdgcn_exp2f(x); }
; DEVINL void ret_block(const Ctx& c, int b, int hd, unsigned char* lds) {
;     ...
; #pragma unroll 2
;             for (int ks = 0; ks < 8; ++ks) {
;                 const bf16x8 vf = *(const bf16x8*)(va + 16 * ks);
;                 const u32x4 kr = *(const u32x4*)(kb + 16 * ks);
;                 u32x4 kd;
; #pragma unroll
;                 for (int jj = 0; jj < 4; ++jj) {
;                     const int j0 = 16 * ks + 8 * h + 2 * jj;
;                     kd[jj] = cvt_pk_bf16(bflo(kr[jj]) * fexp2(lg2 * (float)(127 - j0)), bfhi(kr[jj]) * fexp2(lg2 * (float)(126 - j0)));
;                 }
;                 sacc = MFMA32(vf, __builtin_bit_cast(bf16x8, kd), sacc);
;             }
	v_add_u32_e32 v32, 63, v126
	v_add_u32_e32 v33, 62, v126
	v_cvt_f32_u32_e32 v32, v32
	v_cvt_f32_u32_e32 v33, v33
	v_lshlrev_b32_e32 v34, 16, v176
	v_and_b32_e32 v35, 0xffff0000, v176
	v_mul_f32_e32 v32, v93, v32
	v_mul_f32_e32 v33, v93, v33
	v_exp_f32_e32 v32, v32
	v_exp_f32_e32 v33, v33
	s_nop 0
	v_pk_mul_f32 v[32:33], v[32:33], v[34:35]
	s_nop 0
	v_cvt_pk_bf16_f32 v176, v32, v33
	v_add_u32_e32 v32, 61, v126
	v_add_u32_e32 v33, 60, v126
	v_cvt_f32_u32_e32 v32, v32
	v_cvt_f32_u32_e32 v33, v33
	v_lshlrev_b32_e32 v34, 16, v177
	v_and_b32_e32 v35, 0xffff0000, v177
	v_mul_f32_e32 v32, v93, v32
	v_mul_f32_e32 v33, v93, v33
	v_exp_f32_e32 v32, v32
	v_exp_f32_e32 v33, v33
	s_nop 0
	v_pk_mul_f32 v[32:33], v[32:33], v[34:35]
	s_nop 0
	v_cvt_pk_bf16_f32 v177, v32, v33
	v_add_u32_e32 v32, 59, v126
	v_add_u32_e32 v33, 58, v126
	v_cvt_f32_u32_e32 v32, v32
	v_cvt_f32_u32_e32 v33, v33
	v_lshlrev_b32_e32 v34, 16, v178
	v_and_b32_e32 v35, 0xffff0000, v178
	v_mul_f32_e32 v32, v93, v32
	v_mul_f32_e32 v33, v93, v33
	v_exp_f32_e32 v32, v32
	v_exp_f32_e32 v33, v33
	s_nop 0
	v_pk_mul_f32 v[32:33], v[32:33], v[34:35]
	s_nop 0
	v_cvt_pk_bf16_f32 v178, v32, v33
	v_add_u32_e32 v32, 57, v126
	v_add_u32_e32 v33, 56, v126
	v_cvt_f32_u32_e32 v32, v32
	v_cvt_f32_u32_e32 v33, v33
	v_lshlrev_b32_e32 v34, 16, v179
	v_and_b32_e32 v35, 0xffff0000, v179
	v_mul_f32_e32 v32, v93, v32
	v_mul_f32_e32 v33, v93, v33
	v_exp_f32_e32 v32, v32
	v_exp_f32_e32 v33, v33
	s_nop 0
	v_pk_mul_f32 v[32:33], v[32:33], v[34:35]
	s_nop 0
	v_cvt_pk_bf16_f32 v179, v32, v33
	s_nop 1
	v_mfma_f32_32x32x16_bf16 v[0:15], v[172:175], v[176:179], v[0:15]
	s_waitcnt vmcnt(12)
	v_add_u32_e32 v32, 47, v126
	v_add_u32_e32 v33, 46, v126
	v_cvt_f32_u32_e32 v32, v32
	v_cvt_f32_u32_e32 v33, v33
	v_lshlrev_b32_e32 v34, 16, v208
	v_and_b32_e32 v35, 0xffff0000, v208
	v_mul_f32_e32 v32, v93, v32
	v_mul_f32_e32 v33, v93, v33
	v_exp_f32_e32 v32, v32
	v_exp_f32_e32 v33, v33
	s_nop 0
	v_pk_mul_f32 v[32:33], v[32:33], v[34:35]
	s_nop 0
	v_cvt_pk_bf16_f32 v208, v32, v33
	v_add_u32_e32 v32, 45, v126
	v_add_u32_e32 v33, 44, v126
	v_cvt_f32_u32_e32 v32, v32
	v_cvt_f32_u32_e32 v33, v33
	v_lshlrev_b32_e32 v34, 16, v209
	v_and_b32_e32 v35, 0xffff0000, v209
	v_mul_f32_e32 v32, v93, v32
	v_mul_f32_e32 v33, v93, v33
	v_exp_f32_e32 v32, v32
	v_exp_f32_e32 v33, v33
	s_nop 0
	v_pk_mul_f32 v[32:33], v[32:33], v[34:35]
	s_nop 0
	v_cvt_pk_bf16_f32 v209, v32, v33
	v_add_u32_e32 v32, 43, v126
	v_add_u32_e32 v33, 42, v126
	v_cvt_f32_u32_e32 v32, v32
	v_cvt_f32_u32_e32 v33, v33
	v_lshlrev_b32_e32 v34, 16, v210
	v_and_b32_e32 v35, 0xffff0000, v210
	v_mul_f32_e32 v32, v93, v32
	v_mul_f32_e32 v33, v93, v33
	v_exp_f32_e32 v32, v32
	v_exp_f32_e32 v33, v33
	s_nop 0
	v_pk_mul_f32 v[32:33], v[32:33], v[34:35]
	s_nop 0
	v_cvt_pk_bf16_f32 v210, v32, v33
	v_add_u32_e32 v32, 41, v126
	v_add_u32_e32 v33, 40, v126
	v_cvt_f32_u32_e32 v32, v32
	v_cvt_f32_u32_e32 v33, v33
	v_lshlrev_b32_e32 v34, 16, v211
	v_and_b32_e32 v35, 0xffff0000, v211
	v_mul_f32_e32 v32, v93, v32
	v_mul_f32_e32 v33, v93, v33
	v_exp_f32_e32 v32, v32
	v_exp_f32_e32 v33, v33
	s_nop 0
	v_pk_mul_f32 v[32:33], v[32:33], v[34:35]
	s_nop 0
	v_cvt_pk_bf16_f32 v211, v32, v33
	s_nop 1
	v_mfma_f32_32x32x16_bf16 v[0:15], v[180:183], v[208:211], v[0:15]
	s_waitcnt vmcnt(10)
	v_add_u32_e32 v32, 31, v126
	v_add_u32_e32 v33, 30, v126
	v_cvt_f32_u32_e32 v32, v32
	v_cvt_f32_u32_e32 v33, v33
	v_lshlrev_b32_e32 v34, 16, v216
	v_and_b32_e32 v35, 0xffff0000, v216
	v_mul_f32_e32 v32, v93, v32
	v_mul_f32_e32 v33, v93, v33
	v_exp_f32_e32 v32, v32
	v_exp_f32_e32 v33, v33
	s_nop 0
	v_pk_mul_f32 v[32:33], v[32:33], v[34:35]
	s_nop 0
	v_cvt_pk_bf16_f32 v216, v32, v33
	v_add_u32_e32 v32, 29, v126
	v_add_u32_e32 v33, 28, v126
	v_cvt_f32_u32_e32 v32, v32
	v_cvt_f32_u32_e32 v33, v33
	v_lshlrev_b32_e32 v34, 16, v217
	v_and_b32_e32 v35, 0xffff0000, v217
	v_mul_f32_e32 v32, v93, v32
	v_mul_f32_e32 v33, v93, v33
	v_exp_f32_e32 v32, v32
	v_exp_f32_e32 v33, v33
	s_nop 0
	v_pk_mul_f32 v[32:33], v[32:33], v[34:35]
	s_nop 0
	v_cvt_pk_bf16_f32 v217, v32, v33
	v_add_u32_e32 v32, 27, v126
	v_add_u32_e32 v33, 26, v126
	v_cvt_f32_u32_e32 v32, v32
	v_cvt_f32_u32_e32 v33, v33
	v_lshlrev_b32_e32 v34, 16, v218
	v_and_b32_e32 v35, 0xffff0000, v218
	v_mul_f32_e32 v32, v93, v32
	v_mul_f32_e32 v33, v93, v33
	v_exp_f32_e32 v32, v32
	v_exp_f32_e32 v33, v33
	s_nop 0
	v_pk_mul_f32 v[32:33], v[32:33], v[34:35]
	s_nop 0
	v_cvt_pk_bf16_f32 v218, v32, v33
	v_add_u32_e32 v32, 25, v126
	v_add_u32_e32 v33, 24, v126
	v_cvt_f32_u32_e32 v32, v32
	v_cvt_f32_u32_e32 v33, v33
	v_lshlrev_b32_e32 v34, 16, v219
	v_and_b32_e32 v35, 0xffff0000, v219
	v_mul_f32_e32 v32, v93, v32
	v_mul_f32_e32 v33, v93, v33
	v_exp_f32_e32 v32, v32
	v_exp_f32_e32 v33, v33
	s_nop 0
	v_pk_mul_f32 v[32:33], v[32:33], v[34:35]
	s_nop 0
	v_cvt_pk_bf16_f32 v219, v32, v33
	s_nop 1
	v_mfma_f32_32x32x16_bf16 v[0:15], v[212:215], v[216:219], v[0:15]
	s_waitcnt vmcnt(8)
	v_add_u32_e32 v32, 15, v126
	v_add_u32_e32 v33, 14, v126
	v_cvt_f32_u32_e32 v32, v32
	v_cvt_f32_u32_e32 v33, v33
	v_lshlrev_b32_e32 v34, 16, v224
	v_and_b32_e32 v35, 0xffff0000, v224
	v_mul_f32_e32 v32, v93, v32
	v_mul_f32_e32 v33, v93, v33
	v_exp_f32_e32 v32, v32
	v_exp_f32_e32 v33, v33
	s_nop 0
	v_pk_mul_f32 v[32:33], v[32:33], v[34:35]
	s_nop 0
	v_cvt_pk_bf16_f32 v224, v32, v33
	v_add_u32_e32 v32, 13, v126
	v_add_u32_e32 v33, 12, v126
	v_cvt_f32_u32_e32 v32, v32
	v_cvt_f32_u32_e32 v33, v33
	v_lshlrev_b32_e32 v34, 16, v225
	v_and_b32_e32 v35, 0xffff0000, v225
	v_mul_f32_e32 v32, v93, v32
	v_mul_f32_e32 v33, v93, v33
	v_exp_f32_e32 v32, v32
	v_exp_f32_e32 v33, v33
	s_nop 0
	v_pk_mul_f32 v[32:33], v[32:33], v[34:35]
	s_nop 0
	v_cvt_pk_bf16_f32 v225, v32, v33
	v_add_u32_e32 v32, 11, v126
	v_add_u32_e32 v33, 10, v126
	v_cvt_f32_u32_e32 v32, v32
	v_cvt_f32_u32_e32 v33, v33
	v_lshlrev_b32_e32 v34, 16, v226
	v_and_b32_e32 v35, 0xffff0000, v226
	v_mul_f32_e32 v32, v93, v32
	v_mul_f32_e32 v33, v93, v33
	v_exp_f32_e32 v32, v32
	v_exp_f32_e32 v33, v33
	s_nop 0
	v_pk_mul_f32 v[32:33], v[32:33], v[34:35]
	s_nop 0
	v_cvt_pk_bf16_f32 v226, v32, v33
	v_add_u32_e32 v32, 9, v126
	v_add_u32_e32 v33, 8, v126
	v_cvt_f32_u32_e32 v32, v32
	v_cvt_f32_u32_e32 v33, v33
	v_lshlrev_b32_e32 v34, 16, v227
	v_and_b32_e32 v35, 0xffff0000, v227
	v_mul_f32_e32 v32, v93, v32
	v_mul_f32_e32 v33, v93, v33
	v_exp_f32_e32 v32, v32
	v_exp_f32_e32 v33, v33
	s_nop 0
	v_pk_mul_f32 v[32:33], v[32:33], v[34:35]
	s_nop 0
	v_cvt_pk_bf16_f32 v227, v32, v33
	s_nop 1
	v_mfma_f32_32x32x16_bf16 v[0:15], v[220:223], v[224:227], v[0:15]
	s_add_i32 s7, s7, 1
	v_add_u32_e32 v125, 0x80, v125
	v_lshl_add_u64 v[108:109], v[108:109], 0, s[84:85]
	v_lshl_add_u64 v[110:111], v[110:111], 0, s[84:85]
	v_lshl_add_u64 v[112:113], v[112:113], 0, s[84:85]
	s_cmp_eq_u32 s7, 17
	v_lshl_add_u64 v[114:115], v[114:115], 0, s[84:85]
	s_cbranch_scc0 .LBB0_268
; DEVINL void group_barrier(unsigned* word, unsigned target) {
;     asm volatile("s_waitcnt vmcnt(0) lgkmcnt(0)" ::: "memory");
;     __syncthreads();
;     if (threadIdx.x == 0) {
;         __builtin_amdgcn_fence(__ATOMIC_RELEASE, "agent");
;         __hip_atomic_fetch_add(word, 1u, __ATOMIC_RELAXED, __HIP_MEMORY_SCOPE_AGENT);
;         while (__hip_atomic_load(word, __ATOMIC_RELAXED, __HIP_MEMORY_SCOPE_AGENT) < target) __builtin_amdgcn_s_sleep(2);
.LBB0_275:
	s_waitcnt vmcnt(0) lgkmcnt(0)
	s_waitcnt vmcnt(0)
	s_barrier
	s_mov_b64 s[0:1], exec
	v_readlane_b32 s4, v246, 33
	v_readlane_b32 s5, v246, 34
	s_and_b64 s[4:5], s[0:1], s[4:5]
	s_mov_b64 exec, s[4:5]
	s_cbranch_execz .LBB0_281
	s_mov_b64 s[4:5], exec
	v_mbcnt_lo_u32_b32 v0, s4, 0
	v_mbcnt_hi_u32_b32 v0, s5, v0
	v_cmp_eq_u32_e32 vcc, 0, v0
	s_nop 0
	s_and_saveexec_b64 s[6:7], vcc
	v_readlane_b32 s10, v247, 55
	v_readlane_b32 s11, v247, 56
	s_cbranch_execz .LBB0_278
	s_bcnt1_i32_b64 s4, s[4:5]
	v_mov_b32_e32 v0, s4
	s_nop 1
	global_atomic_add v65, v0, s[10:11]
